# ya group-norm moved out of phase 4 into the (memory-idle) prompt prep waves of the RWKV scan phase
# speedup vs baseline: 1.0564x; 1.0215x over previous
.LBB0_1015:
	s_cmp_eq_u32 s48, 0x100
	s_cbranch_scc1 .LBB0_1032
	s_cmpk_gt_i32 s48, 0x60
	s_cselect_b32 s0, 48, 0
	s_cmp_lt_i32 s2, s0
	s_cbranch_scc1 .LBB0_1032
	s_add_i32 s1, 0, 0x20070
	v_mov_b32_e32 v1, s1
	ds_read_b64 v[2:3], v1
	s_sub_i32 s1, s2, s0
	s_mov_b32 s3, 0x440000
	v_lshl_add_u32 v1, s1, 9, v178
	v_cmp_gt_u32_e32 vcc, s3, v1
	s_waitcnt lgkmcnt(0)
	v_readfirstlane_b32 s10, v2
	v_readfirstlane_b32 s11, v3
	s_and_saveexec_b64 s[12:13], vcc
	s_cbranch_execz .LBB0_1031
	s_add_u32 s16, s46, 0x5200000
	s_addc_u32 s17, s47, 0
	s_lshl_b32 s1, s48, 10
	s_mul_i32 s4, s0, 0x600
	s_sub_i32 s20, s1, s4
	s_lshl_b32 s1, s48, 11
	s_lshl_b32 s4, s0, 11
	s_sub_i32 s21, s1, s4
	s_mul_i32 s1, s48, 0x600
	s_sub_i32 s22, s1, s4
	s_lshl_b32 s1, s0, 9
	v_mov_b32_e32 v3, 0
	s_sub_i32 s23, 0, s1
	s_lshl_b32 s1, s48, 9
	s_lshl_b32 s4, s0, 10
	v_mov_b32_e32 v4, v3
	v_mov_b32_e32 v5, v3
	s_sub_i32 s24, s1, s4
	s_lshl_b32 s1, s48, 14
	s_lshl_b32 s0, s0, 14
	v_mov_b64_e32 v[6:7], v[4:5]
	v_lshlrev_b32_e32 v1, 3, v1
	s_sub_i32 s25, s1, s0
	s_mov_b64 s[18:19], 0
	v_mov_b32_e32 v28, 0x3727c5ac
	s_mov_b32 s26, 0x800000
	s_mov_b32 s27, 0x43ffff
	v_mov_b32_e32 v29, v232
	v_mov_b64_e32 v[4:5], v[2:3]
	v_mov_b32_e32 v8, v3
	v_mov_b32_e32 v9, v3
	v_mov_b32_e32 v10, v3
	v_mov_b32_e32 v11, v3
	v_mov_b32_e32 v12, v3
	v_mov_b32_e32 v13, v3
	v_mov_b32_e32 v14, v3
	v_mov_b32_e32 v15, v3
	v_mov_b32_e32 v16, v3
	v_mov_b32_e32 v17, v3
	v_mov_b32_e32 v18, v3
	v_mov_b32_e32 v19, v3
	s_branch .LBB0_1019

.Lrwq_noq0_a:
	s_add_u32 s0, s0, 0x5200
	s_addc_u32 s1, s1, 0
	global_load_short_d16_hi v100, v175, s[0:1] offset:-2048
	global_load_short_d16_hi v108, v175, s[0:1]
	global_load_short_d16_hi v116, v175, s[0:1] offset:2048
	s_add_u32 s0, s0, 0x5200
	s_addc_u32 s1, s1, 0
	global_load_short_d16_hi v101, v175, s[0:1] offset:-2048
	global_load_short_d16_hi v109, v175, s[0:1]
	global_load_short_d16_hi v117, v175, s[0:1] offset:2048
	s_add_u32 s0, s0, 0x5200
	s_addc_u32 s1, s1, 0
	global_load_short_d16_hi v102, v175, s[0:1] offset:-2048
	global_load_short_d16_hi v110, v175, s[0:1]
	global_load_short_d16_hi v118, v175, s[0:1] offset:2048
	s_add_u32 s0, s0, 0x5200
	s_addc_u32 s1, s1, 0
	global_load_short_d16_hi v103, v175, s[0:1] offset:-2048
	global_load_short_d16_hi v111, v175, s[0:1]
	global_load_short_d16_hi v119, v175, s[0:1] offset:2048
	s_add_u32 s0, s0, 0x5200
	s_addc_u32 s1, s1, 0
	global_load_short_d16_hi v104, v175, s[0:1] offset:-2048
	global_load_short_d16_hi v112, v175, s[0:1]
	global_load_short_d16_hi v120, v175, s[0:1] offset:2048
	s_add_u32 s0, s0, 0x5200
	s_addc_u32 s1, s1, 0
	global_load_short_d16_hi v105, v175, s[0:1] offset:-2048
	global_load_short_d16_hi v113, v175, s[0:1]
	global_load_short_d16_hi v121, v175, s[0:1] offset:2048
	s_add_u32 s0, s0, 0x5200
	s_addc_u32 s1, s1, 0
	global_load_short_d16_hi v106, v175, s[0:1] offset:-2048
	global_load_short_d16_hi v114, v175, s[0:1]
	global_load_short_d16_hi v122, v175, s[0:1] offset:2048
	s_add_u32 s0, s0, 0x5200
	s_addc_u32 s1, s1, 0
	global_load_short_d16_hi v107, v175, s[0:1] offset:-2048
	global_load_short_d16_hi v115, v175, s[0:1]
	global_load_short_d16_hi v123, v175, s[0:1] offset:2048
	s_add_u32 s0, s100, 0x0
	s_addc_u32 s1, s101, 0
	global_load_short_d16_hi v124, v175, s[0:1]
	global_load_short_d16_hi v125, v175, s[0:1] offset:2048
	s_add_u32 s0, s58, 0x0
	s_addc_u32 s1, s59, 0
	global_load_short_d16_hi v132, v175, s[0:1]
	global_load_short_d16_hi v133, v175, s[0:1] offset:2048
	s_add_u32 s0, s100, 0x1000
	s_addc_u32 s1, s101, 0
	global_load_short_d16_hi v126, v175, s[0:1]
	global_load_short_d16_hi v127, v175, s[0:1] offset:2048
	s_add_u32 s0, s58, 0x1000
	s_addc_u32 s1, s59, 0
	global_load_short_d16_hi v134, v175, s[0:1]
	global_load_short_d16_hi v135, v175, s[0:1] offset:2048
	s_add_u32 s0, s100, 0x2000
	s_addc_u32 s1, s101, 0
	global_load_short_d16_hi v128, v175, s[0:1]
	global_load_short_d16_hi v129, v175, s[0:1] offset:2048
	s_add_u32 s0, s58, 0x2000
	s_addc_u32 s1, s59, 0
	global_load_short_d16_hi v136, v175, s[0:1]
	global_load_short_d16_hi v137, v175, s[0:1] offset:2048
	s_add_u32 s0, s100, 0x3000
	s_addc_u32 s1, s101, 0
	global_load_short_d16_hi v130, v175, s[0:1]
	global_load_short_d16_hi v131, v175, s[0:1] offset:2048
	s_add_u32 s0, s58, 0x3000
	s_addc_u32 s1, s59, 0
	global_load_short_d16_hi v138, v175, s[0:1]
	global_load_short_d16_hi v139, v175, s[0:1] offset:2048
	global_load_dwordx4 v[140:143], v77, s[60:61] offset:-4
	global_load_dwordx4 v[144:147], v77, s[60:61] offset:252
	global_load_dwordx4 v[148:151], v77, s[60:61] offset:508
	global_load_dwordx4 v[152:155], v77, s[60:61] offset:764
	global_load_dwordx4 v[156:159], v77, s[60:61] offset:1020
	global_load_dwordx4 v[160:163], v77, s[60:61] offset:1276
	global_load_dwordx4 v[164:167], v77, s[60:61] offset:1532
	global_load_dwordx4 v[168:171], v77, s[60:61] offset:1788
	s_add_u32 s98, s98, 0xa4000
	s_addc_u32 s99, s99, 0
	s_add_u32 s100, s100, 0x10000
	s_addc_u32 s101, s101, 0
	s_add_u32 s58, s58, 0x10000
	s_addc_u32 s59, s59, 0
	s_add_u32 s60, s60, 0x2000
	s_addc_u32 s61, s61, 0
	s_waitcnt vmcnt(0)
	v_sub_f32_e32 v221, 1.0, v200
	s_mov_b32 s0, 0
	s_waitcnt vmcnt(0)
	v_add_u32_e32 v222, s0, v224
	v_add_u32_e32 v223, s0, v225
	v_mul_f32_e32 v204, 0xbfb8aa3b, v124
	v_mul_f32_e32 v205, 0x3fb8aa3b, v124
	v_sub_f32_e32 v208, v172, v100
	v_exp_f32_e32 v211, v204
	v_exp_f32_e32 v212, v205
	v_sub_f32_e32 v209, v173, v108
	v_sub_f32_e32 v210, v174, v116
	v_fma_f32 v208, v196, v208, v100
	v_fma_f32 v209, v197, v209, v108
	v_fma_f32 v210, v198, v210, v116
	v_mul_f32_e32 v213, v209, v199
	v_fma_f32 v214, v132, v200, v221
	v_mul_f32_e32 v213, v213, v141
	v_mul_f32_e32 v215, v209, v214
	v_mul_f32_e32 v217, -1.0, v213
	v_mul_f32_e32 v216, v213, v132
	v_mul_f32_e32 v218, v211, v208
	v_fmac_f32_e32 v218, v142, v217
	ds_write2st64_b32 v222, v217, v218 offset0:0 offset1:1
	v_mul_f32_e32 v219, v216, v212
	v_mul_f32_e32 v220, v215, v212
	ds_write2st64_b32 v222, v211, v219 offset0:2 offset1:3
	ds_write_b32 v222, v220 offset:1024
	ds_write_b32 v223, v210 offset:0
	ds_write_b32 v223, v143 offset:8
	v_mul_f32_e32 v204, 0xbfb8aa3b, v125
	v_mul_f32_e32 v205, 0x3fb8aa3b, v125
	v_sub_f32_e32 v208, v100, v101
	v_exp_f32_e32 v206, v204
	v_exp_f32_e32 v207, v205
	v_sub_f32_e32 v209, v108, v109
	v_sub_f32_e32 v210, v116, v117
	v_fma_f32 v208, v196, v208, v101
	v_fma_f32 v209, v197, v209, v109
	v_fma_f32 v210, v198, v210, v117
	v_mul_f32_e32 v213, v209, v199
	v_fma_f32 v214, v133, v200, v221
	v_mul_f32_e32 v213, v213, v145
	v_mul_f32_e32 v215, v209, v214
	v_mul_f32_e64 v217, -v213, v211
	v_mul_f32_e32 v211, v211, v206
	v_mul_f32_e32 v212, v212, v207
	v_mul_f32_e32 v216, v213, v133
	v_mul_f32_e32 v218, v211, v208
	v_fmac_f32_e32 v218, v146, v217
	ds_write2st64_b32 v222, v217, v218 offset0:7 offset1:8
	v_mul_f32_e32 v219, v216, v212
	v_mul_f32_e32 v220, v215, v212
	ds_write2st64_b32 v222, v211, v219 offset0:9 offset1:10
	ds_write_b32 v222, v220 offset:2816
	ds_write_b32 v223, v210 offset:1792
	ds_write_b32 v223, v147 offset:1800
	v_mul_f32_e32 v204, 0xbfb8aa3b, v126
	v_mul_f32_e32 v205, 0x3fb8aa3b, v126
	v_sub_f32_e32 v208, v101, v102
	v_exp_f32_e32 v206, v204
	v_exp_f32_e32 v207, v205
	v_sub_f32_e32 v209, v109, v110
	v_sub_f32_e32 v210, v117, v118
	v_fma_f32 v208, v196, v208, v102
	v_fma_f32 v209, v197, v209, v110
	v_fma_f32 v210, v198, v210, v118
	v_mul_f32_e32 v213, v209, v199
	v_fma_f32 v214, v134, v200, v221
	v_mul_f32_e32 v213, v213, v149
	v_mul_f32_e32 v215, v209, v214
	v_mul_f32_e64 v217, -v213, v211
	v_mul_f32_e32 v211, v211, v206
	v_mul_f32_e32 v212, v212, v207
	v_mul_f32_e32 v216, v213, v134
	v_mul_f32_e32 v218, v211, v208
	v_fmac_f32_e32 v218, v150, v217
	ds_write2st64_b32 v222, v217, v218 offset0:14 offset1:15
	v_mul_f32_e32 v219, v216, v212
	v_mul_f32_e32 v220, v215, v212
	ds_write2st64_b32 v222, v211, v219 offset0:16 offset1:17
	ds_write_b32 v222, v220 offset:4608
	ds_write_b32 v223, v210 offset:3584
	ds_write_b32 v223, v151 offset:3592
	v_mul_f32_e32 v204, 0xbfb8aa3b, v127
	v_mul_f32_e32 v205, 0x3fb8aa3b, v127
	v_sub_f32_e32 v208, v102, v103
	v_exp_f32_e32 v206, v204
	v_exp_f32_e32 v207, v205
	v_sub_f32_e32 v209, v110, v111
	v_sub_f32_e32 v210, v118, v119
	v_fma_f32 v208, v196, v208, v103
	v_fma_f32 v209, v197, v209, v111
	v_fma_f32 v210, v198, v210, v119
	v_mul_f32_e32 v213, v209, v199
	v_fma_f32 v214, v135, v200, v221
	v_mul_f32_e32 v213, v213, v153
	v_mul_f32_e32 v215, v209, v214
	v_mul_f32_e64 v217, -v213, v211
	v_mul_f32_e32 v211, v211, v206
	v_mul_f32_e32 v212, v212, v207
	v_mul_f32_e32 v216, v213, v135
	v_mul_f32_e32 v218, v211, v208
	v_fmac_f32_e32 v218, v154, v217
	ds_write2st64_b32 v222, v217, v218 offset0:21 offset1:22
	v_mul_f32_e32 v219, v216, v212
	v_mul_f32_e32 v220, v215, v212
	ds_write2st64_b32 v222, v211, v219 offset0:23 offset1:24
	ds_write_b32 v222, v220 offset:6400
	ds_write_b32 v223, v210 offset:5376
	ds_write_b32 v223, v155 offset:5384
	v_mul_f32_e32 v204, 0xbfb8aa3b, v128
	v_mul_f32_e32 v205, 0x3fb8aa3b, v128
	v_sub_f32_e32 v208, v103, v104
	v_exp_f32_e32 v206, v204
	v_exp_f32_e32 v207, v205
	v_sub_f32_e32 v209, v111, v112
	v_sub_f32_e32 v210, v119, v120
	v_fma_f32 v208, v196, v208, v104
	v_fma_f32 v209, v197, v209, v112
	v_fma_f32 v210, v198, v210, v120
	v_mul_f32_e32 v213, v209, v199
	v_fma_f32 v214, v136, v200, v221
	v_mul_f32_e32 v213, v213, v157
	v_mul_f32_e32 v215, v209, v214
	v_mul_f32_e64 v217, -v213, v211
	v_mul_f32_e32 v211, v211, v206
	v_mul_f32_e32 v212, v212, v207
	v_mul_f32_e32 v216, v213, v136
	v_mul_f32_e32 v218, v211, v208
	v_fmac_f32_e32 v218, v158, v217
	ds_write2st64_b32 v222, v217, v218 offset0:28 offset1:29
	v_mul_f32_e32 v219, v216, v212
	v_mul_f32_e32 v220, v215, v212
	ds_write2st64_b32 v222, v211, v219 offset0:30 offset1:31
	ds_write_b32 v222, v220 offset:8192
	ds_write_b32 v223, v210 offset:7168
	ds_write_b32 v223, v159 offset:7176
	v_mul_f32_e32 v204, 0xbfb8aa3b, v129
	v_mul_f32_e32 v205, 0x3fb8aa3b, v129
	v_sub_f32_e32 v208, v104, v105
	v_exp_f32_e32 v206, v204
	v_exp_f32_e32 v207, v205
	v_sub_f32_e32 v209, v112, v113
	v_sub_f32_e32 v210, v120, v121
	v_fma_f32 v208, v196, v208, v105
	v_fma_f32 v209, v197, v209, v113
	v_fma_f32 v210, v198, v210, v121
	v_mul_f32_e32 v213, v209, v199
	v_fma_f32 v214, v137, v200, v221
	v_mul_f32_e32 v213, v213, v161
	v_mul_f32_e32 v215, v209, v214
	v_mul_f32_e64 v217, -v213, v211
	v_mul_f32_e32 v211, v211, v206
	v_mul_f32_e32 v212, v212, v207
	v_mul_f32_e32 v216, v213, v137
	v_mul_f32_e32 v218, v211, v208
	v_fmac_f32_e32 v218, v162, v217
	ds_write2st64_b32 v222, v217, v218 offset0:35 offset1:36
	v_mul_f32_e32 v219, v216, v212
	v_mul_f32_e32 v220, v215, v212
	ds_write2st64_b32 v222, v211, v219 offset0:37 offset1:38
	ds_write_b32 v222, v220 offset:9984
	ds_write_b32 v223, v210 offset:8960
	ds_write_b32 v223, v163 offset:8968
	v_mul_f32_e32 v204, 0xbfb8aa3b, v130
	v_mul_f32_e32 v205, 0x3fb8aa3b, v130
	v_sub_f32_e32 v208, v105, v106
	v_exp_f32_e32 v206, v204
	v_exp_f32_e32 v207, v205
	v_sub_f32_e32 v209, v113, v114
	v_sub_f32_e32 v210, v121, v122
	v_fma_f32 v208, v196, v208, v106
	v_fma_f32 v209, v197, v209, v114
	v_fma_f32 v210, v198, v210, v122
	v_mul_f32_e32 v213, v209, v199
	v_fma_f32 v214, v138, v200, v221
	v_mul_f32_e32 v213, v213, v165
	v_mul_f32_e32 v215, v209, v214
	v_mul_f32_e64 v217, -v213, v211
	v_mul_f32_e32 v211, v211, v206
	v_mul_f32_e32 v212, v212, v207
	v_mul_f32_e32 v216, v213, v138
	v_mul_f32_e32 v218, v211, v208
	v_fmac_f32_e32 v218, v166, v217
	ds_write2st64_b32 v222, v217, v218 offset0:42 offset1:43
	v_mul_f32_e32 v219, v216, v212
	v_mul_f32_e32 v220, v215, v212
	ds_write2st64_b32 v222, v211, v219 offset0:44 offset1:45
	ds_write_b32 v222, v220 offset:11776
	ds_write_b32 v223, v210 offset:10752
	ds_write_b32 v223, v167 offset:10760
	v_mul_f32_e32 v204, 0xbfb8aa3b, v131
	v_mul_f32_e32 v205, 0x3fb8aa3b, v131
	v_sub_f32_e32 v208, v106, v107
	v_exp_f32_e32 v206, v204
	v_exp_f32_e32 v207, v205
	v_sub_f32_e32 v209, v114, v115
	v_sub_f32_e32 v210, v122, v123
	v_fma_f32 v208, v196, v208, v107
	v_fma_f32 v209, v197, v209, v115
	v_fma_f32 v210, v198, v210, v123
	v_mul_f32_e32 v213, v209, v199
	v_fma_f32 v214, v139, v200, v221
	v_mul_f32_e32 v213, v213, v169
	v_mul_f32_e32 v215, v209, v214
	v_mul_f32_e64 v217, -v213, v211
	v_mul_f32_e32 v211, v211, v206
	v_mul_f32_e32 v212, v212, v207
	v_mul_f32_e32 v216, v213, v139
	v_mul_f32_e32 v218, v211, v208
	v_fmac_f32_e32 v218, v170, v217
	ds_write2st64_b32 v222, v217, v218 offset0:49 offset1:50
	v_mul_f32_e32 v219, v216, v212
	v_mul_f32_e32 v220, v215, v212
	ds_write2st64_b32 v222, v211, v219 offset0:51 offset1:52
	ds_write_b32 v222, v220 offset:13568
	ds_write_b32 v223, v210 offset:12544
	ds_write_b32 v223, v171 offset:12552
	s_sub_u32 s0, s98, 0x5200
	s_subb_u32 s1, s99, 0
	global_load_short_d16_hi v172, v175, s[0:1] offset:-2048
	global_load_short_d16_hi v173, v175, s[0:1]
	global_load_short_d16_hi v174, v175, s[0:1] offset:2048
	s_add_u32 s0, s0, 0x5200
	s_addc_u32 s1, s1, 0
	global_load_short_d16_hi v100, v175, s[0:1] offset:-2048
	global_load_short_d16_hi v108, v175, s[0:1]
	global_load_short_d16_hi v116, v175, s[0:1] offset:2048
	s_add_u32 s0, s0, 0x5200
	s_addc_u32 s1, s1, 0
	global_load_short_d16_hi v101, v175, s[0:1] offset:-2048
	global_load_short_d16_hi v109, v175, s[0:1]
	global_load_short_d16_hi v117, v175, s[0:1] offset:2048
	s_add_u32 s0, s0, 0x5200
	s_addc_u32 s1, s1, 0
	global_load_short_d16_hi v102, v175, s[0:1] offset:-2048
	global_load_short_d16_hi v110, v175, s[0:1]
	global_load_short_d16_hi v118, v175, s[0:1] offset:2048
	s_add_u32 s0, s0, 0x5200
	s_addc_u32 s1, s1, 0
	global_load_short_d16_hi v103, v175, s[0:1] offset:-2048
	global_load_short_d16_hi v111, v175, s[0:1]
	global_load_short_d16_hi v119, v175, s[0:1] offset:2048
	s_add_u32 s0, s0, 0x5200
	s_addc_u32 s1, s1, 0
	global_load_short_d16_hi v104, v175, s[0:1] offset:-2048
	global_load_short_d16_hi v112, v175, s[0:1]
	global_load_short_d16_hi v120, v175, s[0:1] offset:2048
	s_add_u32 s0, s0, 0x5200
	s_addc_u32 s1, s1, 0
	global_load_short_d16_hi v105, v175, s[0:1] offset:-2048
	global_load_short_d16_hi v113, v175, s[0:1]
	global_load_short_d16_hi v121, v175, s[0:1] offset:2048
	s_add_u32 s0, s0, 0x5200
	s_addc_u32 s1, s1, 0
	global_load_short_d16_hi v106, v175, s[0:1] offset:-2048
	global_load_short_d16_hi v114, v175, s[0:1]
	global_load_short_d16_hi v122, v175, s[0:1] offset:2048
	s_add_u32 s0, s0, 0x5200
	s_addc_u32 s1, s1, 0
	global_load_short_d16_hi v107, v175, s[0:1] offset:-2048
	global_load_short_d16_hi v115, v175, s[0:1]
	global_load_short_d16_hi v123, v175, s[0:1] offset:2048
	s_add_u32 s0, s100, 0x0
	s_addc_u32 s1, s101, 0
	global_load_short_d16_hi v124, v175, s[0:1]
	global_load_short_d16_hi v125, v175, s[0:1] offset:2048
	s_add_u32 s0, s58, 0x0
	s_addc_u32 s1, s59, 0
	global_load_short_d16_hi v132, v175, s[0:1]
	global_load_short_d16_hi v133, v175, s[0:1] offset:2048
	s_add_u32 s0, s100, 0x1000
	s_addc_u32 s1, s101, 0
	global_load_short_d16_hi v126, v175, s[0:1]
	global_load_short_d16_hi v127, v175, s[0:1] offset:2048
	s_add_u32 s0, s58, 0x1000
	s_addc_u32 s1, s59, 0
	global_load_short_d16_hi v134, v175, s[0:1]
	global_load_short_d16_hi v135, v175, s[0:1] offset:2048
	s_add_u32 s0, s100, 0x2000
	s_addc_u32 s1, s101, 0
	global_load_short_d16_hi v128, v175, s[0:1]
	global_load_short_d16_hi v129, v175, s[0:1] offset:2048
	s_add_u32 s0, s58, 0x2000
	s_addc_u32 s1, s59, 0
	global_load_short_d16_hi v136, v175, s[0:1]
	global_load_short_d16_hi v137, v175, s[0:1] offset:2048
	s_add_u32 s0, s100, 0x3000
	s_addc_u32 s1, s101, 0
	global_load_short_d16_hi v130, v175, s[0:1]
	global_load_short_d16_hi v131, v175, s[0:1] offset:2048
	s_add_u32 s0, s58, 0x3000
	s_addc_u32 s1, s59, 0
	global_load_short_d16_hi v138, v175, s[0:1]
	global_load_short_d16_hi v139, v175, s[0:1] offset:2048
	global_load_dwordx4 v[140:143], v77, s[60:61] offset:-4
	global_load_dwordx4 v[144:147], v77, s[60:61] offset:252
	global_load_dwordx4 v[148:151], v77, s[60:61] offset:508
	global_load_dwordx4 v[152:155], v77, s[60:61] offset:764
	global_load_dwordx4 v[156:159], v77, s[60:61] offset:1020
	global_load_dwordx4 v[160:163], v77, s[60:61] offset:1276
	global_load_dwordx4 v[164:167], v77, s[60:61] offset:1532
	global_load_dwordx4 v[168:171], v77, s[60:61] offset:1788
	s_add_u32 s98, s98, 0xa4000
	s_addc_u32 s99, s99, 0
	s_add_u32 s100, s100, 0x10000
	s_addc_u32 s101, s101, 0
	s_add_u32 s58, s58, 0x10000
	s_addc_u32 s59, s59, 0
	s_add_u32 s60, s60, 0x2000
	s_addc_u32 s61, s61, 0
	s_cmp_eq_u32 s48, 0x100
	s_cbranch_scc0 .Lya_pre_skip
	v_add_u32_e32 v233, -4, v179
	v_lshl_add_u32 v233, v233, 6, v1
	v_mov_b32_e32 v246, 0x20070
	ds_read_b64 v[242:243], v246
	v_lshlrev_b32_e32 v230, 5, v233
	v_lshlrev_b32_e32 v233, 4, v233
	s_waitcnt lgkmcnt(0)
	v_readfirstlane_b32 s52, v242
	v_readfirstlane_b32 s53, v243
	s_nop 4
	global_load_dwordx4 v[234:237], v230, s[52:53]
	global_load_dwordx4 v[238:241], v230, s[52:53] offset:16
	s_mov_b32 s55, 0
	s_lshl_b32 s54, s55, 9
	s_add_u32 s54, s54, s2
	s_mul_i32 s52, s54, 0x5200
	s_add_u32 s52, s20, s52
	s_addc_u32 s53, s21, 0
	global_load_dwordx4 v[242:245], v233, s[52:53]
	s_add_u32 s52, s52, 0x520000
	s_addc_u32 s53, s53, 0
	global_load_dwordx4 v[226:229], v233, s[52:53]
	s_lshl_b32 s52, s54, 4
	s_lshl_b32 s53, s33, 2
	s_add_u32 s52, s52, s53
	s_add_u32 s52, s46, s52
	s_addc_u32 s53, s47, 0
	global_load_dword v247, v77, s[52:53]
	s_add_u32 s52, s52, 0x1000
	s_addc_u32 s53, s53, 0
	global_load_dword v248, v77, s[52:53]
.Lya_pre_skip:
.LBB0_1345:
	s_or_b64 exec, exec, s[56:57]
	s_and_b32 s0, s63, 0xfffff800
	s_lshl_b32 s30, s72, 5
	s_mul_hi_i32 s1, s0, 0x5200
	s_mulk_i32 s0, 0x5200
	v_and_or_b32 v201, s30, 32, v164
	s_and_b32 s30, s41, 0x780
	s_or_b32 s0, s0, s30
	v_and_or_b32 v5, s65, 32, v164
	s_add_u32 s0, s3, s0
	v_lshlrev_b32_e32 v12, 1, v5
	v_mov_b32_e32 v13, v77
	s_waitcnt lgkmcnt(0)
	s_barrier
	s_addc_u32 s1, s62, s1
	v_lshlrev_b32_e32 v76, 1, v42
	v_lshl_add_u64 v[88:89], s[0:1], 0, v[12:13]
	v_mov_b32_e32 v12, v77
	v_lshlrev_b32_e32 v202, 2, v5
	v_lshl_add_u64 v[84:85], s[22:23], 0, v[76:77]
	v_lshl_add_u64 v[86:87], v[10:11], 2, s[28:29]
	s_mov_b32 s30, 0
	v_mov_b64_e32 v[10:11], v[12:13]
	v_mov_b64_e32 v[16:17], v[12:13]
	v_mov_b64_e32 v[14:15], v[12:13]
	s_branch .LBB0_1348

.LBB0_1348:
	s_and_saveexec_b64 s[0:1], s[16:17]
	s_xor_b64 s[56:57], exec, s[0:1]
	s_cbranch_execz .LBB0_1368
	s_cmp_eq_u32 s30, 63
	s_cbranch_scc1 .LBB0_1368
	s_andn2_b32 s0, 1, s30
	s_mul_i32 s0, s0, 0xe000
	s_waitcnt vmcnt(0)
	v_add_u32_e32 v222, s0, v224
	v_add_u32_e32 v223, s0, v225
	v_mul_f32_e32 v204, 0xbfb8aa3b, v124
	v_mul_f32_e32 v205, 0x3fb8aa3b, v124
	v_sub_f32_e32 v208, v172, v100
	v_exp_f32_e32 v211, v204
	v_exp_f32_e32 v212, v205
	v_sub_f32_e32 v209, v173, v108
	v_sub_f32_e32 v210, v174, v116
	v_fma_f32 v208, v196, v208, v100
	v_fma_f32 v209, v197, v209, v108
	v_fma_f32 v210, v198, v210, v116
	v_mul_f32_e32 v213, v209, v199
	v_fma_f32 v214, v132, v200, v221
	v_mul_f32_e32 v213, v213, v141
	v_mul_f32_e32 v215, v209, v214
	v_mul_f32_e32 v217, -1.0, v213
	v_mul_f32_e32 v216, v213, v132
	v_mul_f32_e32 v218, v211, v208
	v_fmac_f32_e32 v218, v142, v217
	ds_write2st64_b32 v222, v217, v218 offset0:0 offset1:1
	v_mul_f32_e32 v219, v216, v212
	v_mul_f32_e32 v220, v215, v212
	ds_write2st64_b32 v222, v211, v219 offset0:2 offset1:3
	ds_write_b32 v222, v220 offset:1024
	ds_write_b32 v223, v210 offset:0
	ds_write_b32 v223, v143 offset:8
	v_mul_f32_e32 v204, 0xbfb8aa3b, v125
	v_mul_f32_e32 v205, 0x3fb8aa3b, v125
	v_sub_f32_e32 v208, v100, v101
	v_exp_f32_e32 v206, v204
	v_exp_f32_e32 v207, v205
	v_sub_f32_e32 v209, v108, v109
	v_sub_f32_e32 v210, v116, v117
	v_fma_f32 v208, v196, v208, v101
	v_fma_f32 v209, v197, v209, v109
	v_fma_f32 v210, v198, v210, v117
	v_mul_f32_e32 v213, v209, v199
	v_fma_f32 v214, v133, v200, v221
	v_mul_f32_e32 v213, v213, v145
	v_mul_f32_e32 v215, v209, v214
	v_mul_f32_e64 v217, -v213, v211
	v_mul_f32_e32 v211, v211, v206
	v_mul_f32_e32 v212, v212, v207
	v_mul_f32_e32 v216, v213, v133
	v_mul_f32_e32 v218, v211, v208
	v_fmac_f32_e32 v218, v146, v217
	ds_write2st64_b32 v222, v217, v218 offset0:7 offset1:8
	v_mul_f32_e32 v219, v216, v212
	v_mul_f32_e32 v220, v215, v212
	ds_write2st64_b32 v222, v211, v219 offset0:9 offset1:10
	ds_write_b32 v222, v220 offset:2816
	ds_write_b32 v223, v210 offset:1792
	ds_write_b32 v223, v147 offset:1800
	v_mul_f32_e32 v204, 0xbfb8aa3b, v126
	v_mul_f32_e32 v205, 0x3fb8aa3b, v126
	v_sub_f32_e32 v208, v101, v102
	v_exp_f32_e32 v206, v204
	v_exp_f32_e32 v207, v205
	v_sub_f32_e32 v209, v109, v110
	v_sub_f32_e32 v210, v117, v118
	v_fma_f32 v208, v196, v208, v102
	v_fma_f32 v209, v197, v209, v110
	v_fma_f32 v210, v198, v210, v118
	v_mul_f32_e32 v213, v209, v199
	v_fma_f32 v214, v134, v200, v221
	v_mul_f32_e32 v213, v213, v149
	v_mul_f32_e32 v215, v209, v214
	v_mul_f32_e64 v217, -v213, v211
	v_mul_f32_e32 v211, v211, v206
	v_mul_f32_e32 v212, v212, v207
	v_mul_f32_e32 v216, v213, v134
	v_mul_f32_e32 v218, v211, v208
	v_fmac_f32_e32 v218, v150, v217
	ds_write2st64_b32 v222, v217, v218 offset0:14 offset1:15
	v_mul_f32_e32 v219, v216, v212
	v_mul_f32_e32 v220, v215, v212
	ds_write2st64_b32 v222, v211, v219 offset0:16 offset1:17
	ds_write_b32 v222, v220 offset:4608
	ds_write_b32 v223, v210 offset:3584
	ds_write_b32 v223, v151 offset:3592
	v_mul_f32_e32 v204, 0xbfb8aa3b, v127
	v_mul_f32_e32 v205, 0x3fb8aa3b, v127
	v_sub_f32_e32 v208, v102, v103
	v_exp_f32_e32 v206, v204
	v_exp_f32_e32 v207, v205
	v_sub_f32_e32 v209, v110, v111
	v_sub_f32_e32 v210, v118, v119
	v_fma_f32 v208, v196, v208, v103
	v_fma_f32 v209, v197, v209, v111
	v_fma_f32 v210, v198, v210, v119
	v_mul_f32_e32 v213, v209, v199
	v_fma_f32 v214, v135, v200, v221
	v_mul_f32_e32 v213, v213, v153
	v_mul_f32_e32 v215, v209, v214
	v_mul_f32_e64 v217, -v213, v211
	v_mul_f32_e32 v211, v211, v206
	v_mul_f32_e32 v212, v212, v207
	v_mul_f32_e32 v216, v213, v135
	v_mul_f32_e32 v218, v211, v208
	v_fmac_f32_e32 v218, v154, v217
	ds_write2st64_b32 v222, v217, v218 offset0:21 offset1:22
	v_mul_f32_e32 v219, v216, v212
	v_mul_f32_e32 v220, v215, v212
	ds_write2st64_b32 v222, v211, v219 offset0:23 offset1:24
	ds_write_b32 v222, v220 offset:6400
	ds_write_b32 v223, v210 offset:5376
	ds_write_b32 v223, v155 offset:5384
	v_mul_f32_e32 v204, 0xbfb8aa3b, v128
	v_mul_f32_e32 v205, 0x3fb8aa3b, v128
	v_sub_f32_e32 v208, v103, v104
	v_exp_f32_e32 v206, v204
	v_exp_f32_e32 v207, v205
	v_sub_f32_e32 v209, v111, v112
	v_sub_f32_e32 v210, v119, v120
	v_fma_f32 v208, v196, v208, v104
	v_fma_f32 v209, v197, v209, v112
	v_fma_f32 v210, v198, v210, v120
	v_mul_f32_e32 v213, v209, v199
	v_fma_f32 v214, v136, v200, v221
	v_mul_f32_e32 v213, v213, v157
	v_mul_f32_e32 v215, v209, v214
	v_mul_f32_e64 v217, -v213, v211
	v_mul_f32_e32 v211, v211, v206
	v_mul_f32_e32 v212, v212, v207
	v_mul_f32_e32 v216, v213, v136
	v_mul_f32_e32 v218, v211, v208
	v_fmac_f32_e32 v218, v158, v217
	ds_write2st64_b32 v222, v217, v218 offset0:28 offset1:29
	v_mul_f32_e32 v219, v216, v212
	v_mul_f32_e32 v220, v215, v212
	ds_write2st64_b32 v222, v211, v219 offset0:30 offset1:31
	ds_write_b32 v222, v220 offset:8192
	ds_write_b32 v223, v210 offset:7168
	ds_write_b32 v223, v159 offset:7176
	v_mul_f32_e32 v204, 0xbfb8aa3b, v129
	v_mul_f32_e32 v205, 0x3fb8aa3b, v129
	v_sub_f32_e32 v208, v104, v105
	v_exp_f32_e32 v206, v204
	v_exp_f32_e32 v207, v205
	v_sub_f32_e32 v209, v112, v113
	v_sub_f32_e32 v210, v120, v121
	v_fma_f32 v208, v196, v208, v105
	v_fma_f32 v209, v197, v209, v113
	v_fma_f32 v210, v198, v210, v121
	v_mul_f32_e32 v213, v209, v199
	v_fma_f32 v214, v137, v200, v221
	v_mul_f32_e32 v213, v213, v161
	v_mul_f32_e32 v215, v209, v214
	v_mul_f32_e64 v217, -v213, v211
	v_mul_f32_e32 v211, v211, v206
	v_mul_f32_e32 v212, v212, v207
	v_mul_f32_e32 v216, v213, v137
	v_mul_f32_e32 v218, v211, v208
	v_fmac_f32_e32 v218, v162, v217
	ds_write2st64_b32 v222, v217, v218 offset0:35 offset1:36
	v_mul_f32_e32 v219, v216, v212
	v_mul_f32_e32 v220, v215, v212
	ds_write2st64_b32 v222, v211, v219 offset0:37 offset1:38
	ds_write_b32 v222, v220 offset:9984
	ds_write_b32 v223, v210 offset:8960
	ds_write_b32 v223, v163 offset:8968
	v_mul_f32_e32 v204, 0xbfb8aa3b, v130
	v_mul_f32_e32 v205, 0x3fb8aa3b, v130
	v_sub_f32_e32 v208, v105, v106
	v_exp_f32_e32 v206, v204
	v_exp_f32_e32 v207, v205
	v_sub_f32_e32 v209, v113, v114
	v_sub_f32_e32 v210, v121, v122
	v_fma_f32 v208, v196, v208, v106
	v_fma_f32 v209, v197, v209, v114
	v_fma_f32 v210, v198, v210, v122
	v_mul_f32_e32 v213, v209, v199
	v_fma_f32 v214, v138, v200, v221
	v_mul_f32_e32 v213, v213, v165
	v_mul_f32_e32 v215, v209, v214
	v_mul_f32_e64 v217, -v213, v211
	v_mul_f32_e32 v211, v211, v206
	v_mul_f32_e32 v212, v212, v207
	v_mul_f32_e32 v216, v213, v138
	v_mul_f32_e32 v218, v211, v208
	v_fmac_f32_e32 v218, v166, v217
	ds_write2st64_b32 v222, v217, v218 offset0:42 offset1:43
	v_mul_f32_e32 v219, v216, v212
	v_mul_f32_e32 v220, v215, v212
	ds_write2st64_b32 v222, v211, v219 offset0:44 offset1:45
	ds_write_b32 v222, v220 offset:11776
	ds_write_b32 v223, v210 offset:10752
	ds_write_b32 v223, v167 offset:10760
	v_mul_f32_e32 v204, 0xbfb8aa3b, v131
	v_mul_f32_e32 v205, 0x3fb8aa3b, v131
	v_sub_f32_e32 v208, v106, v107
	v_exp_f32_e32 v206, v204
	v_exp_f32_e32 v207, v205
	v_sub_f32_e32 v209, v114, v115
	v_sub_f32_e32 v210, v122, v123
	v_fma_f32 v208, v196, v208, v107
	v_fma_f32 v209, v197, v209, v115
	v_fma_f32 v210, v198, v210, v123
	v_mul_f32_e32 v213, v209, v199
	v_fma_f32 v214, v139, v200, v221
	v_mul_f32_e32 v213, v213, v169
	v_mul_f32_e32 v215, v209, v214
	v_mul_f32_e64 v217, -v213, v211
	v_mul_f32_e32 v211, v211, v206
	v_mul_f32_e32 v212, v212, v207
	v_mul_f32_e32 v216, v213, v139
	v_mul_f32_e32 v218, v211, v208
	v_fmac_f32_e32 v218, v170, v217
	ds_write2st64_b32 v222, v217, v218 offset0:49 offset1:50
	v_mul_f32_e32 v219, v216, v212
	v_mul_f32_e32 v220, v215, v212
	ds_write2st64_b32 v222, v211, v219 offset0:51 offset1:52
	ds_write_b32 v222, v220 offset:13568
	ds_write_b32 v223, v210 offset:12544
	ds_write_b32 v223, v171 offset:12552
	s_cmp_gt_u32 s30, 33
	s_cbranch_scc1 .Lya_done
	s_cmp_eq_u32 s48, 0x100
	s_cbranch_scc0 .Lya_done
	v_mul_f32_e32 v247, 0x3b000000, v247
	v_add_f32_e32 v247, 0x3727c5ac, v247
	v_rsq_f32_e32 v247, v247
	v_lshlrev_b32_e32 v230, 16, v242
	v_and_b32_e32 v231, 0xffff0000, v242
	v_mul_f32_e32 v246, v247, v234
	v_mul_f32_e32 v230, v230, v246
	v_mul_f32_e32 v246, v247, v235
	v_mul_f32_e32 v231, v231, v246
	v_cvt_pk_bf16_f32 v242, v230, v231
	v_lshlrev_b32_e32 v230, 16, v243
	v_and_b32_e32 v231, 0xffff0000, v243
	v_mul_f32_e32 v246, v247, v236
	v_mul_f32_e32 v230, v230, v246
	v_mul_f32_e32 v246, v247, v237
	v_mul_f32_e32 v231, v231, v246
	v_cvt_pk_bf16_f32 v243, v230, v231
	v_lshlrev_b32_e32 v230, 16, v244
	v_and_b32_e32 v231, 0xffff0000, v244
	v_mul_f32_e32 v246, v247, v238
	v_mul_f32_e32 v230, v230, v246
	v_mul_f32_e32 v246, v247, v239
	v_mul_f32_e32 v231, v231, v246
	v_cvt_pk_bf16_f32 v244, v230, v231
	v_lshlrev_b32_e32 v230, 16, v245
	v_and_b32_e32 v231, 0xffff0000, v245
	v_mul_f32_e32 v246, v247, v240
	v_mul_f32_e32 v230, v230, v246
	v_mul_f32_e32 v246, v247, v241
	v_mul_f32_e32 v231, v231, v246
	v_cvt_pk_bf16_f32 v245, v230, v231
	v_mul_f32_e32 v248, 0x3b000000, v248
	v_add_f32_e32 v248, 0x3727c5ac, v248
	v_rsq_f32_e32 v248, v248
	v_lshlrev_b32_e32 v230, 16, v226
	v_and_b32_e32 v231, 0xffff0000, v226
	v_mul_f32_e32 v246, v248, v234
	v_mul_f32_e32 v230, v230, v246
	v_mul_f32_e32 v246, v248, v235
	v_mul_f32_e32 v231, v231, v246
	v_cvt_pk_bf16_f32 v226, v230, v231
	v_lshlrev_b32_e32 v230, 16, v227
	v_and_b32_e32 v231, 0xffff0000, v227
	v_mul_f32_e32 v246, v248, v236
	v_mul_f32_e32 v230, v230, v246
	v_mul_f32_e32 v246, v248, v237
	v_mul_f32_e32 v231, v231, v246
	v_cvt_pk_bf16_f32 v227, v230, v231
	v_lshlrev_b32_e32 v230, 16, v228
	v_and_b32_e32 v231, 0xffff0000, v228
	v_mul_f32_e32 v246, v248, v238
	v_mul_f32_e32 v230, v230, v246
	v_mul_f32_e32 v246, v248, v239
	v_mul_f32_e32 v231, v231, v246
	v_cvt_pk_bf16_f32 v228, v230, v231
	v_lshlrev_b32_e32 v230, 16, v229
	v_and_b32_e32 v231, 0xffff0000, v229
	v_mul_f32_e32 v246, v248, v240
	v_mul_f32_e32 v230, v230, v246
	v_mul_f32_e32 v246, v248, v241
	v_mul_f32_e32 v231, v231, v246
	v_cvt_pk_bf16_f32 v229, v230, v231
	s_mov_b32 s55, s30
	s_lshl_b32 s54, s55, 9
	s_add_u32 s54, s54, s2
	s_mul_i32 s52, s54, 0x5200
	s_add_u32 s52, s20, s52
	s_addc_u32 s53, s21, 0
	global_store_dwordx4 v233, v[242:245], s[52:53]
	s_add_u32 s52, s52, 0x520000
	s_addc_u32 s53, s53, 0
	global_store_dwordx4 v233, v[226:229], s[52:53]
	s_cmp_eq_u32 s30, 33
	s_cbranch_scc1 .Lya_done
	s_add_u32 s55, s30, 1
	s_lshl_b32 s54, s55, 9
	s_add_u32 s54, s54, s2
	s_mul_i32 s52, s54, 0x5200
	s_add_u32 s52, s20, s52
	s_addc_u32 s53, s21, 0
	global_load_dwordx4 v[242:245], v233, s[52:53]
	s_add_u32 s52, s52, 0x520000
	s_addc_u32 s53, s53, 0
	global_load_dwordx4 v[226:229], v233, s[52:53]
	s_lshl_b32 s52, s54, 4
	s_lshl_b32 s53, s33, 2
	s_add_u32 s52, s52, s53
	s_add_u32 s52, s46, s52
	s_addc_u32 s53, s47, 0
	global_load_dword v247, v77, s[52:53]
	s_add_u32 s52, s52, 0x1000
	s_addc_u32 s53, s53, 0
	global_load_dword v248, v77, s[52:53]
.Lya_done:
	s_cmp_gt_u32 s30, 61
	s_cbranch_scc1 .LBB0_1368
	s_sub_u32 s0, s98, 0x5200
	s_subb_u32 s1, s99, 0
	global_load_short_d16_hi v172, v175, s[0:1] offset:-2048
	global_load_short_d16_hi v173, v175, s[0:1]
	global_load_short_d16_hi v174, v175, s[0:1] offset:2048
	s_add_u32 s0, s0, 0x5200
	s_addc_u32 s1, s1, 0
	global_load_short_d16_hi v100, v175, s[0:1] offset:-2048
	global_load_short_d16_hi v108, v175, s[0:1]
	global_load_short_d16_hi v116, v175, s[0:1] offset:2048
	s_add_u32 s0, s0, 0x5200
	s_addc_u32 s1, s1, 0
	global_load_short_d16_hi v101, v175, s[0:1] offset:-2048
	global_load_short_d16_hi v109, v175, s[0:1]
	global_load_short_d16_hi v117, v175, s[0:1] offset:2048
	s_add_u32 s0, s0, 0x5200
	s_addc_u32 s1, s1, 0
	global_load_short_d16_hi v102, v175, s[0:1] offset:-2048
	global_load_short_d16_hi v110, v175, s[0:1]
	global_load_short_d16_hi v118, v175, s[0:1] offset:2048
	s_add_u32 s0, s0, 0x5200
	s_addc_u32 s1, s1, 0
	global_load_short_d16_hi v103, v175, s[0:1] offset:-2048
	global_load_short_d16_hi v111, v175, s[0:1]
	global_load_short_d16_hi v119, v175, s[0:1] offset:2048
	s_add_u32 s0, s0, 0x5200
	s_addc_u32 s1, s1, 0
	global_load_short_d16_hi v104, v175, s[0:1] offset:-2048
	global_load_short_d16_hi v112, v175, s[0:1]
	global_load_short_d16_hi v120, v175, s[0:1] offset:2048
	s_add_u32 s0, s0, 0x5200
	s_addc_u32 s1, s1, 0
	global_load_short_d16_hi v105, v175, s[0:1] offset:-2048
	global_load_short_d16_hi v113, v175, s[0:1]
	global_load_short_d16_hi v121, v175, s[0:1] offset:2048
	s_add_u32 s0, s0, 0x5200
	s_addc_u32 s1, s1, 0
	global_load_short_d16_hi v106, v175, s[0:1] offset:-2048
	global_load_short_d16_hi v114, v175, s[0:1]
	global_load_short_d16_hi v122, v175, s[0:1] offset:2048
	s_add_u32 s0, s0, 0x5200
	s_addc_u32 s1, s1, 0
	global_load_short_d16_hi v107, v175, s[0:1] offset:-2048
	global_load_short_d16_hi v115, v175, s[0:1]
	global_load_short_d16_hi v123, v175, s[0:1] offset:2048
	s_add_u32 s0, s100, 0x0
	s_addc_u32 s1, s101, 0
	global_load_short_d16_hi v124, v175, s[0:1]
	global_load_short_d16_hi v125, v175, s[0:1] offset:2048
	s_add_u32 s0, s58, 0x0
	s_addc_u32 s1, s59, 0
	global_load_short_d16_hi v132, v175, s[0:1]
	global_load_short_d16_hi v133, v175, s[0:1] offset:2048
	s_add_u32 s0, s100, 0x1000
	s_addc_u32 s1, s101, 0
	global_load_short_d16_hi v126, v175, s[0:1]
	global_load_short_d16_hi v127, v175, s[0:1] offset:2048
	s_add_u32 s0, s58, 0x1000
	s_addc_u32 s1, s59, 0
	global_load_short_d16_hi v134, v175, s[0:1]
	global_load_short_d16_hi v135, v175, s[0:1] offset:2048
	s_add_u32 s0, s100, 0x2000
	s_addc_u32 s1, s101, 0
	global_load_short_d16_hi v128, v175, s[0:1]
	global_load_short_d16_hi v129, v175, s[0:1] offset:2048
	s_add_u32 s0, s58, 0x2000
	s_addc_u32 s1, s59, 0
	global_load_short_d16_hi v136, v175, s[0:1]
	global_load_short_d16_hi v137, v175, s[0:1] offset:2048
	s_add_u32 s0, s100, 0x3000
	s_addc_u32 s1, s101, 0
	global_load_short_d16_hi v130, v175, s[0:1]
	global_load_short_d16_hi v131, v175, s[0:1] offset:2048
	s_add_u32 s0, s58, 0x3000
	s_addc_u32 s1, s59, 0
	global_load_short_d16_hi v138, v175, s[0:1]
	global_load_short_d16_hi v139, v175, s[0:1] offset:2048
	global_load_dwordx4 v[140:143], v77, s[60:61] offset:-4
	global_load_dwordx4 v[144:147], v77, s[60:61] offset:252
	global_load_dwordx4 v[148:151], v77, s[60:61] offset:508
	global_load_dwordx4 v[152:155], v77, s[60:61] offset:764
	global_load_dwordx4 v[156:159], v77, s[60:61] offset:1020
	global_load_dwordx4 v[160:163], v77, s[60:61] offset:1276
	global_load_dwordx4 v[164:167], v77, s[60:61] offset:1532
	global_load_dwordx4 v[168:171], v77, s[60:61] offset:1788
	s_add_u32 s98, s98, 0xa4000
	s_addc_u32 s99, s99, 0
	s_add_u32 s100, s100, 0x10000
	s_addc_u32 s101, s101, 0
	s_add_u32 s58, s58, 0x10000
	s_addc_u32 s59, s59, 0
	s_add_u32 s60, s60, 0x2000
	s_addc_u32 s61, s61, 0
